# topk: try the previous pair's candidate threshold (with a proportional controller and one cheap retry) before the bit search; exact fallback
# speedup vs baseline: 1.1943x; 1.0032x over previous
; __device__ void topk_unit(const Params& p, unsigned char* smem, int unit) {
;   const int tid = threadIdx.x & 255, lane = tid & 63, wid = tid >> 6, l15 = lane & 15, q4 = lane >> 4;
;   const int h = unit & 7, tile = unit >> 3;
;   const int tok0 = tile * 64 + wid * 16;
;   unsigned char* ws = p.ws;
;   const bf16_t* qg = (const bf16_t*)(ws + OFF_Q);
;   const bf16_t* kb = (const bf16_t*)(ws + OFF_KEYSB);
;   unsigned* S = (unsigned*)(smem + wid * 16640);
;   float* tops = (float*)(smem + 4 * 16640 + wid * 256);
;   int* topi = (int*)(tops + 32);
;   unsigned* Ms = (unsigned*)(smem + 67584 + wid * 768);
; #pragma unroll
;   for (int k = 0; k < 2; ++k) {
;     f32x4 sc[8];
; #pragma unroll
;     for (int i = 0; i < 8; ++i) sc[i] = (f32x4){0, 0, 0, 0};
; #pragma unroll
;     for (int ks = 0; ks < 4; ++ks) {
;       bf16x8 qf = as_frag(*(const u32x4*)(qg + (size_t)(tok0 + l15) * DM + h * 256 + k * 128 + ks * 32 + q4 * 8));
; #pragma unroll
;       for (int nt = 0; nt < 8; ++nt) {
;         bf16x8 kf = as_frag(*(const u32x4*)(kb + (size_t)((h * 2 + k) * 128 + nt * 16 + l15) * 128 + ks * 32 + q4 * 8));
;         sc[nt] = mfma16(kf, qf, sc[nt]);
;       }
;     }
; #pragma unroll
;     for (int nt = 0; nt < 8; ++nt) {
;       const int n = nt * 16 + q4 * 4;
;       u32x4 kk;
; #pragma unroll
;       for (int r = 0; r < 4; ++r) kk[r] = (ord_key(sc[nt][r]) & ~127u) | (unsigned)(127 - (n + r));
;       *(u32x4*)(S + l15 * 260 + k * 128 + n) = kk;
;     }
;   }
;   const unsigned ct = cand_tab[lane];
;   const int ca = ct >> 4, cbb = ct & 15;
;   int* idxo = (int*)(ws + OFF_IDX);
;   float* go = (float*)(ws + OFF_G);
;   for (int tk = 0; tk < 16; ++tk) {
.LBB0_1082:
	s_or_b64 exec, exec, s[10:11]
	s_and_saveexec_b64 s[22:23], s[0:1]
	s_cbranch_execz .LBB0_1130
	s_add_u32 s36, s34, 0x8000000
	s_addc_u32 s37, s35, 0
	s_getpc_b64 s[0:1]
	s_add_u32 s0, s0, _ZL8cand_tab@rel32@lo+4
	s_addc_u32 s1, s1, _ZL8cand_tab@rel32@hi+12
	global_load_ubyte v65, v138, s[0:1]
	s_waitcnt lgkmcnt(0)
	v_lshlrev_b64 v[2:3], v139, -1
	v_mbcnt_lo_u32_b32 v10, -1, 0
	v_mul_lo_u32 v5, s96, v1
	v_bfe_u32 v1, v139, 6, 2
	v_and_b32_e32 v96, 15, v139
	v_bfe_u32 v7, v139, 4, 2
	s_movk_i32 s3, 0x4100
	v_not_b32_e32 v64, v2
	v_mbcnt_hi_u32_b32 v2, -1, v10
	v_and_b32_e32 v62, 48, v139
	v_lshlrev_b32_e32 v12, 2, v138
	v_mad_u32_u24 v13, v1, s3, v166
	v_lshlrev_b32_e32 v6, 3, v7
	v_lshlrev_b32_e32 v98, 2, v7
	v_mul_u32_u24_e32 v7, 0x410, v96
	v_and_b32_e32 v102, 64, v2
	v_mov_b32_e32 v63, 0
	v_lshlrev_b32_e32 v97, 4, v1
	v_lshlrev_b32_e32 v14, 8, v1
	v_mul_u32_u24_e32 v15, 0x300, v1
	v_not_b32_e32 v1, v3
	v_add3_u32 v100, v13, v7, v62
	v_xor_b32_e32 v3, 32, v2
	v_add_u32_e32 v103, v13, v12
	v_add_u32_e32 v13, 64, v102
	s_mov_b64 s[0:1], 0x1d740000
	s_mov_b64 s[6:7], 0x1d740040
	s_mov_b64 s[8:9], 0x1d740080
	s_mov_b64 s[10:11], 0x1d7400c0
	v_lshl_add_u64 v[8:9], s[34:35], 0, v[62:63]
	v_xor_b32_e32 v7, 16, v2
	v_cmp_lt_i32_e32 vcc, v3, v13
	v_lshl_add_u64 v[66:67], v[8:9], 0, s[0:1]
	v_lshl_add_u64 v[68:69], v[8:9], 0, s[6:7]
	v_lshl_add_u64 v[70:71], v[8:9], 0, s[8:9]
	v_lshl_add_u64 v[72:73], v[8:9], 0, s[10:11]
	v_xor_b32_e32 v8, 8, v2
	v_cndmask_b32_e32 v3, v2, v3, vcc
	v_cmp_lt_i32_e32 vcc, v7, v13
	v_xor_b32_e32 v9, 4, v2
	s_mov_b32 s12, 0x10400
	v_cndmask_b32_e32 v7, v2, v7, vcc
	v_cmp_lt_i32_e32 vcc, v8, v13
	v_xor_b32_e32 v10, 2, v2
	v_add3_u32 v99, v166, v14, s12
	v_cndmask_b32_e32 v8, v2, v8, vcc
	v_cmp_lt_i32_e32 vcc, v9, v13
	v_xor_b32_e32 v14, 1, v2
	s_add_u32 s38, s34, 0xc000000
	v_cndmask_b32_e32 v9, v2, v9, vcc
	v_cmp_lt_i32_e32 vcc, v10, v13
	v_lshlrev_b32_e32 v106, 2, v3
	s_addc_u32 s39, s35, 0
	v_cndmask_b32_e32 v10, v2, v10, vcc
	v_cmp_lt_i32_e32 vcc, v14, v13
	s_add_u32 s40, s34, 0xc800000
	s_mov_b32 s13, 0x10800
	v_cndmask_b32_e32 v2, v2, v14, vcc
	v_lshlrev_b32_e32 v111, 2, v2
	s_addc_u32 s41, s35, 0
	v_lshlrev_b32_e32 v74, 3, v5
	s_lshl_b32 s49, s96, 4
	s_lshl_b32 s0, s2, 1
	v_and_b32_e32 v11, 31, v139
	v_lshlrev_b32_e32 v4, 5, v138
	v_add3_u32 v101, v166, v15, s13
	v_lshlrev_b32_e32 v62, 4, v138
	v_ashrrev_i32_e32 v75, 31, v74
	s_mov_b32 s48, 0
	v_cmp_gt_u32_e64 s[14:15], 32, v138
	v_cmp_gt_u32_e64 s[4:5], 50, v138
	v_add_u32_e32 v104, v101, v12
	v_lshl_add_u32 v105, v11, 2, v101
	v_lshlrev_b32_e32 v107, 2, v7
	v_lshlrev_b32_e32 v108, 2, v8
	v_lshlrev_b32_e32 v109, 2, v9
	v_lshlrev_b32_e32 v110, 2, v10
	v_cmp_eq_u32_e64 s[6:7], 0, v138
	v_add_u16_e32 v115, s0, v165
	s_waitcnt vmcnt(0)
	v_lshrrev_b32_e32 v3, 2, v65
	v_and_b32_e32 v2, 15, v65
	v_and_b32_e32 v3, 60, v3
	v_lshl_add_u32 v112, v2, 2, v99
	v_add_u32_e32 v113, v99, v3
	v_lshlrev_b32_e32 v2, 7, v138
	v_mov_b32_e32 v3, v63
	v_lshl_add_u64 v[76:77], s[18:19], 0, v[2:3]
	v_lshlrev_b32_e32 v2, 3, v165
	v_lshl_add_u32 v114, s2, 4, v2
	s_add_u32 s18, s34, 0x1dc90000
	v_lshlrev_b32_e32 v2, 11, v164
	s_addc_u32 s19, s35, 0
	v_lshl_add_u32 v78, s2, 3, v164
	s_lshl_b32 s50, s96, 3
	v_lshlrev_b64 v[80:81], 2, v[74:75]
	v_lshl_add_u64 v[82:83], s[34:35], 0, v[62:63]
	v_lshlrev_b64 v[84:85], 10, v[74:75]
	v_lshl_add_u32 v75, s2, 14, v2
	s_lshl_b32 s51, s96, 14
	v_lshlrev_b32_e32 v116, 14, v5
	s_mov_b64 s[42:43], 0
	s_movk_i32 s52, 0xffc0
	v_lshlrev_b32_e32 v86, 1, v6
	v_mov_b32_e32 v87, v63
	v_lshlrev_b32_e32 v117, 8, v96
	s_movk_i32 s53, 0x4000
	v_bfrev_b32_e32 v118, 1
	s_movk_i32 s54, 0xff80
	s_movk_i32 s55, 0x7f
	s_movk_i32 s56, 0x6f
	s_movk_i32 s57, 0x5f
	s_movk_i32 s58, 0x4f
	s_mov_b32 s59, 0x8000
	s_movk_i32 s60, 0xff00
	s_movk_i32 s61, 0xff
	s_mov_b64 s[44:45], 0x80
	s_movk_i32 s62, 0x3fff
	v_lshlrev_b32_e32 v88, 2, v4
	s_mov_b32 s63, 0xf800000
	v_mov_b32_e32 v119, 0x260
	s_mov_b32 s64, 0xc0e00000
	s_movk_i32 s65, 0x80
	s_movk_i32 s66, 0x7fff
	s_movk_i32 s67, 0x7ff
	v_mov_b32_e32 v120, 0x40e00000
	v_mov_b32_e32 v249, -1
	s_branch .LBB0_1085

; __device__ void topk_unit(const Params& p, unsigned char* smem, int unit) {
;     ...
;   for (int tk = 0; tk < 16; ++tk) {
;     const unsigned* row = S + tk * 260;
;     unsigned ka[2], kb[2], mxk[2];
; #pragma unroll
;     for (int hf = 0; hf < 2; ++hf) {
;       ka[hf] = row[hf * 128 + lane];
;       kb[hf] = row[hf * 128 + 64 + lane];
;       mxk[hf] = ka[hf] > kb[hf] ? ka[hf] : kb[hf];
;       Ms[hf * 96 + lane] = mxk[hf];
;     }
;     int cnt[2][4];
; #pragma unroll
;     for (int hf = 0; hf < 2; ++hf)
; #pragma unroll
;       for (int e = 0; e < 4; ++e) cnt[hf][e] = 0;
; #pragma unroll
;     for (int j = 0; j < 16; ++j)
; #pragma unroll
;       for (int hf = 0; hf < 2; ++hf) {
;         u32x4 x = *(const u32x4*)(Ms + hf * 96 + j * 4);
; #pragma unroll
;         for (int e = 0; e < 4; ++e) cnt[hf][e] += (x[e] > mxk[hf]) ? 1 : 0;
;       }
;     bool ca_[2], cb_[2];
;     int pa[2], pb[2], ncand[2];
;     const unsigned long long lt = (1ull << lane) - 1ull;
; #pragma unroll
;     for (int hf = 0; hf < 2; ++hf) {
;       const int c_ = cnt[hf][0] + cnt[hf][1] + cnt[hf][2] + cnt[hf][3];
;       const unsigned long long bm = __ballot(c_ == 15);
;       const int srcT = __ffsll((long long)bm) - 1;
;       const unsigned T0 = (unsigned)__shfl((int)mxk[hf], srcT);
;       ca_[hf] = ka[hf] >= T0;
;       cb_[hf] = kb[hf] >= T0;
;       const unsigned long long ba = __ballot(ca_[hf]), bb = __ballot(cb_[hf]);
;       const int na = __popcll(ba);
;       pa[hf] = __popcll(ba & lt);
;       pb[hf] = na + __popcll(bb & lt);
;       ncand[hf] = na + __popcll(bb);
;     }
; #pragma unroll
;     for (int hf = 0; hf < 2; ++hf) {
;       unsigned* Cs = Ms + hf * 96 + 64;
;       if (lane < 32) Cs[lane] = 0u;
;       if (ca_[hf]) Cs[pa[hf]] = ka[hf];
;       if (cb_[hf]) Cs[pb[hf]] = kb[hf];
;     }
;     unsigned my[2];
;     int rk2[2][4];
; #pragma unroll
;     for (int hf = 0; hf < 2; ++hf) {
;       my[hf] = Ms[hf * 96 + 64 + (lane & 31)];
; #pragma unroll
;       for (int e = 0; e < 4; ++e) rk2[hf][e] = 0;
;     }
; #pragma unroll
;     for (int j = 0; j < 8; ++j)
; #pragma unroll
;       for (int hf = 0; hf < 2; ++hf) {
;         u32x4 x = *(const u32x4*)(Ms + hf * 96 + 64 + j * 4);
; #pragma unroll
;         for (int e = 0; e < 4; ++e) rk2[hf][e] += (x[e] > my[hf]) ? 1 : 0;
;       }
; #pragma unroll
;     for (int hf = 0; hf < 2; ++hf) {
.LBB0_1087:
	v_readlane_b32 s8, v249, 0
	v_readlane_b32 s9, v249, 1
	s_mov_b64 s[46:47], exec
	v_lshrrev_b32_e32 v89, 5, v138
	v_lshlrev_b32_e32 v94, 6, v89
	v_mul_u32_u24_e32 v89, 0x180, v89
	v_add_u32_e32 v94, v99, v94
	v_add_u32_e32 v79, v101, v89
	v_add_u32_e32 v89, v105, v89
	v_sub_u32_e32 v92, 0xff, v65
	s_mov_b32 s3, 0xffffff00
.Ltk2_loop:
	v_add_u32_e32 v8, s12, v103
	ds_read2st64_b32 v[2:3], v8 offset1:1
	ds_read2st64_b32 v[4:5], v8 offset0:2 offset1:3
	s_mov_b32 s84, s8
	s_mov_b32 s85, s9
	s_mov_b32 s10, 0
	s_waitcnt lgkmcnt(0)
.Ltk_stepD:
	s_nop 1
	v_cmp_ge_u32_e64 s[86:87], v2, s84
	v_cmp_ge_u32_e64 s[88:89], v3, s84
	v_cmp_ge_u32_e64 s[68:69], v4, s85
	v_cmp_ge_u32_e64 s[70:71], v5, s85
	s_nop 1
	s_bcnt1_i32_b64 s72, s[86:87]
	s_bcnt1_i32_b64 s73, s[68:69]
	s_bcnt1_i32_b64 s0, s[88:89]
	s_bcnt1_i32_b64 s1, s[70:71]
	s_add_i32 s0, s0, s72
	s_add_i32 s1, s1, s73
	s_sub_u32 s0, s0, 16
	s_sub_u32 s1, s1, 16
	s_max_u32 s11, s0, s1
	s_cmp_gt_u32 s11, 16
	s_cbranch_scc1 .Ltk_retry
	s_sub_i32 s0, s0, 8
	s_sub_i32 s1, s1, 8
	s_lshl_b32 s0, s0, 16
	s_lshl_b32 s1, s1, 16
	s_add_i32 s8, s84, s0
	s_add_i32 s9, s85, s1
	v_mbcnt_lo_u32_b32 v44, s86, 0
	v_mbcnt_lo_u32_b32 v45, s88, 0
	v_mbcnt_lo_u32_b32 v46, s68, 0
	v_mbcnt_lo_u32_b32 v47, s70, 0
	v_mbcnt_hi_u32_b32 v44, s87, v44
	v_mbcnt_hi_u32_b32 v45, s89, v45
	v_mbcnt_hi_u32_b32 v46, s69, v46
	v_mbcnt_hi_u32_b32 v47, s71, v47
	v_add_u32_e32 v45, s72, v45
	v_add_u32_e32 v47, s73, v47
	v_lshl_add_u32 v44, v44, 2, v101
	v_lshl_add_u32 v45, v45, 2, v101
	v_lshl_add_u32 v46, v46, 2, v101
	v_lshl_add_u32 v47, v47, 2, v101
	s_mov_b64 exec, s[14:15]
	ds_write_b32 v105, v63 offset:256
	ds_write_b32 v105, v63 offset:640
	s_mov_b64 exec, s[86:87]
	ds_write_b32 v44, v2 offset:256
	s_mov_b64 exec, s[88:89]
	ds_write_b32 v45, v3 offset:256
	s_mov_b64 exec, s[68:69]
	ds_write_b32 v46, v4 offset:640
	s_mov_b64 exec, s[70:71]
	ds_write_b32 v47, v5 offset:640
	s_mov_b64 exec, s[46:47]
	ds_read_b32 v48, v89 offset:256
	ds_read_b128 v[12:15], v79 offset:256
	ds_read_b128 v[16:19], v79 offset:272
	ds_read_b128 v[20:23], v79 offset:288
	ds_read_b128 v[24:27], v79 offset:304
	ds_read_b128 v[28:31], v79 offset:320
	ds_read_b128 v[32:35], v79 offset:336
	ds_read_b128 v[36:39], v79 offset:352
	ds_read_b128 v[40:43], v79 offset:368
	v_mov_b32_e32 v49, 0
	v_mov_b32_e32 v50, 0
	s_waitcnt lgkmcnt(0)
	v_cmp_gt_u32_e64 s[68:69], v12, v48
	v_cmp_gt_u32_e64 s[70:71], v13, v48
	v_cmp_gt_u32_e64 s[72:73], v14, v48
	v_cmp_gt_u32_e64 s[74:75], v15, v48
	v_addc_co_u32_e64 v49, s[76:77], 0, v49, s[68:69]
	v_addc_co_u32_e64 v50, s[76:77], 0, v50, s[70:71]
	v_addc_co_u32_e64 v49, s[76:77], 0, v49, s[72:73]
	v_addc_co_u32_e64 v50, s[76:77], 0, v50, s[74:75]
	v_cmp_gt_u32_e64 s[68:69], v16, v48
	v_cmp_gt_u32_e64 s[70:71], v17, v48
	v_cmp_gt_u32_e64 s[72:73], v18, v48
	v_cmp_gt_u32_e64 s[74:75], v19, v48
	v_addc_co_u32_e64 v49, s[76:77], 0, v49, s[68:69]
	v_addc_co_u32_e64 v50, s[76:77], 0, v50, s[70:71]
	v_addc_co_u32_e64 v49, s[76:77], 0, v49, s[72:73]
	v_addc_co_u32_e64 v50, s[76:77], 0, v50, s[74:75]
	v_cmp_gt_u32_e64 s[68:69], v20, v48
	v_cmp_gt_u32_e64 s[70:71], v21, v48
	v_cmp_gt_u32_e64 s[72:73], v22, v48
	v_cmp_gt_u32_e64 s[74:75], v23, v48
	v_addc_co_u32_e64 v49, s[76:77], 0, v49, s[68:69]
	v_addc_co_u32_e64 v50, s[76:77], 0, v50, s[70:71]
	v_addc_co_u32_e64 v49, s[76:77], 0, v49, s[72:73]
	v_addc_co_u32_e64 v50, s[76:77], 0, v50, s[74:75]
	v_cmp_gt_u32_e64 s[68:69], v24, v48
	v_cmp_gt_u32_e64 s[70:71], v25, v48
	v_cmp_gt_u32_e64 s[72:73], v26, v48
	v_cmp_gt_u32_e64 s[74:75], v27, v48
	v_addc_co_u32_e64 v49, s[76:77], 0, v49, s[68:69]
	v_addc_co_u32_e64 v50, s[76:77], 0, v50, s[70:71]
	v_addc_co_u32_e64 v49, s[76:77], 0, v49, s[72:73]
	v_addc_co_u32_e64 v50, s[76:77], 0, v50, s[74:75]
	v_cmp_gt_u32_e64 s[68:69], v28, v48
	v_cmp_gt_u32_e64 s[70:71], v29, v48
	v_cmp_gt_u32_e64 s[72:73], v30, v48
	v_cmp_gt_u32_e64 s[74:75], v31, v48
	v_addc_co_u32_e64 v49, s[76:77], 0, v49, s[68:69]
	v_addc_co_u32_e64 v50, s[76:77], 0, v50, s[70:71]
	v_addc_co_u32_e64 v49, s[76:77], 0, v49, s[72:73]
	v_addc_co_u32_e64 v50, s[76:77], 0, v50, s[74:75]
	v_cmp_gt_u32_e64 s[68:69], v32, v48
	v_cmp_gt_u32_e64 s[70:71], v33, v48
	v_cmp_gt_u32_e64 s[72:73], v34, v48
	v_cmp_gt_u32_e64 s[74:75], v35, v48
	v_addc_co_u32_e64 v49, s[76:77], 0, v49, s[68:69]
	v_addc_co_u32_e64 v50, s[76:77], 0, v50, s[70:71]
	v_addc_co_u32_e64 v49, s[76:77], 0, v49, s[72:73]
	v_addc_co_u32_e64 v50, s[76:77], 0, v50, s[74:75]
	v_cmp_gt_u32_e64 s[68:69], v36, v48
	v_cmp_gt_u32_e64 s[70:71], v37, v48
	v_cmp_gt_u32_e64 s[72:73], v38, v48
	v_cmp_gt_u32_e64 s[74:75], v39, v48
	v_addc_co_u32_e64 v49, s[76:77], 0, v49, s[68:69]
	v_addc_co_u32_e64 v50, s[76:77], 0, v50, s[70:71]
	v_addc_co_u32_e64 v49, s[76:77], 0, v49, s[72:73]
	v_addc_co_u32_e64 v50, s[76:77], 0, v50, s[74:75]
	v_cmp_gt_u32_e64 s[68:69], v40, v48
	v_cmp_gt_u32_e64 s[70:71], v41, v48
	v_cmp_gt_u32_e64 s[72:73], v42, v48
	v_cmp_gt_u32_e64 s[74:75], v43, v48
	v_addc_co_u32_e64 v49, s[76:77], 0, v49, s[68:69]
	v_addc_co_u32_e64 v50, s[76:77], 0, v50, s[70:71]
	v_addc_co_u32_e64 v49, s[76:77], 0, v49, s[72:73]
	v_addc_co_u32_e64 v50, s[76:77], 0, v50, s[74:75]
	v_add_u32_e32 v49, v49, v50
	v_and_b32_e32 v51, 0xffffff80, v48
	v_cmp_gt_u32_e64 s[74:75], 16, v49
	v_ashrrev_i32_e32 v52, 31, v51
	v_and_b32_e32 v53, 0x7f, v48
	v_not_b32_e32 v52, v52
	v_sub_u32_e32 v53, 0x7f, v53
	v_or_b32_e32 v52, 0x80000000, v52
	v_lshl_add_u32 v54, v49, 2, v94
	v_xor_b32_e32 v51, v51, v52
	s_mov_b64 exec, s[74:75]
	ds_write_b32 v54, v51
	ds_write_b32 v54, v53 offset:128
	s_mov_b64 exec, s[46:47]
	ds_read_b32 v121, v113
	ds_read_b32 v122, v112 offset:64
	ds_read2_b32 v[124:125], v99 offset1:16
	ds_read_b32 v126, v113 offset:128
	ds_read_b32 v127, v112 offset:192
	s_waitcnt lgkmcnt(3)
; __device__ void topk_unit(const Params& p, unsigned char* smem, int unit) {
;     ...
;     float cs = 0.f;
;     unsigned ck = 0u;
;     if (lane < 50) {
;       cs = tops[ca] + tops[16 + cbb];
;       ck = (ord_key(cs) & ~255u) | (unsigned)(255 - (ca * 16 + cbb));
;     }
;     int rkA = 0, rkB = 0;
; #pragma unroll
;     for (int j = 0; j < 50; j += 2) {
;       const unsigned oj = (unsigned)__builtin_amdgcn_readlane((int)ck, j);
;       const unsigned oj2 = (unsigned)__builtin_amdgcn_readlane((int)ck, j + 1);
;       rkA += (oj > ck) ? 1 : 0;
;       rkB += (oj2 > ck) ? 1 : 0;
;     }
;     const int rk = rkA + rkB;
;     const float mx = tops[0] + tops[16];
;     const bool sel = (lane < 50) && (rk < 16);
;     const float ev = sel ? __expf(cs - mx) : 0.f;
;     const float sum = wave_sum(ev);
;     if (sel) {
;       const size_t o = (size_t)(tok0 + tk) * 128 + h * 16 + rk;
;       idxo[o] = topi[ca] * 128 + topi[16 + cbb];
;       go[o] = ev * __builtin_amdgcn_rcpf(sum);
;     }
	v_add_f32_e32 v128, v121, v122
	v_mov_b32_e32 v130, 0
	v_ashrrev_i32_e32 v129, 31, v128
	v_mov_b32_e32 v131, 0
	v_or_b32_e32 v129, 0x80000000, v129
	v_xor_b32_e32 v129, v128, v129
	v_and_or_b32 v129, v129, s3, v92
	v_cndmask_b32_e64 v129, 0, v129, s[4:5]
	ds_write_b32 v104, v129
	ds_read_b128 v[12:15], v101
	ds_read_b128 v[16:19], v101 offset:16
	ds_read_b128 v[20:23], v101 offset:32
	ds_read_b128 v[24:27], v101 offset:48
	ds_read_b128 v[28:31], v101 offset:64
	ds_read_b128 v[32:35], v101 offset:80
	ds_read_b128 v[36:39], v101 offset:96
	ds_read_b128 v[40:43], v101 offset:112
	s_waitcnt lgkmcnt(4)
	v_cmp_gt_u32_e64 s[68:69], v12, v129
	v_cmp_gt_u32_e64 s[70:71], v13, v129
	v_cmp_gt_u32_e64 s[72:73], v14, v129
	v_cmp_gt_u32_e64 s[74:75], v15, v129
	v_addc_co_u32_e64 v130, s[76:77], 0, v130, s[68:69]
	v_addc_co_u32_e64 v131, s[76:77], 0, v131, s[70:71]
	v_addc_co_u32_e64 v130, s[76:77], 0, v130, s[72:73]
	v_addc_co_u32_e64 v131, s[76:77], 0, v131, s[74:75]
	v_cmp_gt_u32_e64 s[68:69], v16, v129
	v_cmp_gt_u32_e64 s[70:71], v17, v129
	v_cmp_gt_u32_e64 s[72:73], v18, v129
	v_cmp_gt_u32_e64 s[74:75], v19, v129
	v_addc_co_u32_e64 v130, s[76:77], 0, v130, s[68:69]
	v_addc_co_u32_e64 v131, s[76:77], 0, v131, s[70:71]
	v_addc_co_u32_e64 v130, s[76:77], 0, v130, s[72:73]
	v_addc_co_u32_e64 v131, s[76:77], 0, v131, s[74:75]
	v_cmp_gt_u32_e64 s[68:69], v20, v129
	v_cmp_gt_u32_e64 s[70:71], v21, v129
	v_cmp_gt_u32_e64 s[72:73], v22, v129
	v_cmp_gt_u32_e64 s[74:75], v23, v129
	v_addc_co_u32_e64 v130, s[76:77], 0, v130, s[68:69]
	v_addc_co_u32_e64 v131, s[76:77], 0, v131, s[70:71]
	v_addc_co_u32_e64 v130, s[76:77], 0, v130, s[72:73]
	v_addc_co_u32_e64 v131, s[76:77], 0, v131, s[74:75]
	v_cmp_gt_u32_e64 s[68:69], v24, v129
	v_cmp_gt_u32_e64 s[70:71], v25, v129
	v_cmp_gt_u32_e64 s[72:73], v26, v129
	v_cmp_gt_u32_e64 s[74:75], v27, v129
	v_addc_co_u32_e64 v130, s[76:77], 0, v130, s[68:69]
	v_addc_co_u32_e64 v131, s[76:77], 0, v131, s[70:71]
	v_addc_co_u32_e64 v130, s[76:77], 0, v130, s[72:73]
	v_addc_co_u32_e64 v131, s[76:77], 0, v131, s[74:75]
	ds_read_b128 v[12:15], v101 offset:128
	ds_read_b128 v[16:19], v101 offset:144
	ds_read_b128 v[20:23], v101 offset:160
	ds_read_b128 v[24:27], v101 offset:176
	ds_read_b128 v[148:151], v101 offset:192
	s_waitcnt lgkmcnt(5)
	v_cmp_gt_u32_e64 s[68:69], v28, v129
	v_cmp_gt_u32_e64 s[70:71], v29, v129
	v_cmp_gt_u32_e64 s[72:73], v30, v129
	v_cmp_gt_u32_e64 s[74:75], v31, v129
	v_addc_co_u32_e64 v130, s[76:77], 0, v130, s[68:69]
	v_addc_co_u32_e64 v131, s[76:77], 0, v131, s[70:71]
	v_addc_co_u32_e64 v130, s[76:77], 0, v130, s[72:73]
	v_addc_co_u32_e64 v131, s[76:77], 0, v131, s[74:75]
	v_cmp_gt_u32_e64 s[68:69], v32, v129
	v_cmp_gt_u32_e64 s[70:71], v33, v129
	v_cmp_gt_u32_e64 s[72:73], v34, v129
	v_cmp_gt_u32_e64 s[74:75], v35, v129
	v_addc_co_u32_e64 v130, s[76:77], 0, v130, s[68:69]
	v_addc_co_u32_e64 v131, s[76:77], 0, v131, s[70:71]
	v_addc_co_u32_e64 v130, s[76:77], 0, v130, s[72:73]
	v_addc_co_u32_e64 v131, s[76:77], 0, v131, s[74:75]
	v_cmp_gt_u32_e64 s[68:69], v36, v129
	v_cmp_gt_u32_e64 s[70:71], v37, v129
	v_cmp_gt_u32_e64 s[72:73], v38, v129
	v_cmp_gt_u32_e64 s[74:75], v39, v129
	v_addc_co_u32_e64 v130, s[76:77], 0, v130, s[68:69]
	v_addc_co_u32_e64 v131, s[76:77], 0, v131, s[70:71]
	v_addc_co_u32_e64 v130, s[76:77], 0, v130, s[72:73]
	v_addc_co_u32_e64 v131, s[76:77], 0, v131, s[74:75]
	v_cmp_gt_u32_e64 s[68:69], v40, v129
	v_cmp_gt_u32_e64 s[70:71], v41, v129
	v_cmp_gt_u32_e64 s[72:73], v42, v129
	v_cmp_gt_u32_e64 s[74:75], v43, v129
	v_addc_co_u32_e64 v130, s[76:77], 0, v130, s[68:69]
	v_addc_co_u32_e64 v131, s[76:77], 0, v131, s[70:71]
	v_addc_co_u32_e64 v130, s[76:77], 0, v130, s[72:73]
	v_addc_co_u32_e64 v131, s[76:77], 0, v131, s[74:75]
	s_waitcnt lgkmcnt(0)
	v_cmp_gt_u32_e64 s[68:69], v12, v129
	v_cmp_gt_u32_e64 s[70:71], v13, v129
	v_cmp_gt_u32_e64 s[72:73], v14, v129
	v_cmp_gt_u32_e64 s[74:75], v15, v129
	v_addc_co_u32_e64 v130, s[76:77], 0, v130, s[68:69]
	v_addc_co_u32_e64 v131, s[76:77], 0, v131, s[70:71]
	v_addc_co_u32_e64 v130, s[76:77], 0, v130, s[72:73]
	v_addc_co_u32_e64 v131, s[76:77], 0, v131, s[74:75]
	v_cmp_gt_u32_e64 s[68:69], v16, v129
	v_cmp_gt_u32_e64 s[70:71], v17, v129
	v_cmp_gt_u32_e64 s[72:73], v18, v129
	v_cmp_gt_u32_e64 s[74:75], v19, v129
	v_addc_co_u32_e64 v130, s[76:77], 0, v130, s[68:69]
	v_addc_co_u32_e64 v131, s[76:77], 0, v131, s[70:71]
	v_addc_co_u32_e64 v130, s[76:77], 0, v130, s[72:73]
	v_addc_co_u32_e64 v131, s[76:77], 0, v131, s[74:75]
	v_cmp_gt_u32_e64 s[68:69], v20, v129
	v_cmp_gt_u32_e64 s[70:71], v21, v129
	v_cmp_gt_u32_e64 s[72:73], v22, v129
	v_cmp_gt_u32_e64 s[74:75], v23, v129
	v_addc_co_u32_e64 v130, s[76:77], 0, v130, s[68:69]
	v_addc_co_u32_e64 v131, s[76:77], 0, v131, s[70:71]
	v_addc_co_u32_e64 v130, s[76:77], 0, v130, s[72:73]
	v_addc_co_u32_e64 v131, s[76:77], 0, v131, s[74:75]
	v_cmp_gt_u32_e64 s[68:69], v24, v129
	v_cmp_gt_u32_e64 s[70:71], v25, v129
	v_cmp_gt_u32_e64 s[72:73], v26, v129
	v_cmp_gt_u32_e64 s[74:75], v27, v129
	v_addc_co_u32_e64 v130, s[76:77], 0, v130, s[68:69]
	v_addc_co_u32_e64 v131, s[76:77], 0, v131, s[70:71]
	v_addc_co_u32_e64 v130, s[76:77], 0, v130, s[72:73]
	v_addc_co_u32_e64 v131, s[76:77], 0, v131, s[74:75]
	v_cmp_gt_u32_e64 s[68:69], v148, v129
	v_cmp_gt_u32_e64 s[70:71], v149, v129
	v_cmp_gt_u32_e64 s[72:73], v150, v129
	v_cmp_gt_u32_e64 s[74:75], v151, v129
	v_addc_co_u32_e64 v130, s[76:77], 0, v130, s[68:69]
	v_addc_co_u32_e64 v131, s[76:77], 0, v131, s[70:71]
	v_addc_co_u32_e64 v130, s[76:77], 0, v130, s[72:73]
	v_addc_co_u32_e64 v131, s[76:77], 0, v131, s[74:75]
	v_add_u32_e32 v130, v130, v131
	v_mov_b32_e32 v131, 0
	v_cmp_gt_u32_e64 s[78:79], 16, v130
	v_add_f32_e32 v132, v124, v125
	v_sub_f32_e32 v132, v128, v132
	s_and_b64 s[78:79], s[78:79], s[4:5]
	v_mul_f32_e32 v132, 0x3fb8aa3b, v132
	v_exp_f32_e32 v132, v132
	v_lshl_add_u32 v136, v126, 7, v127
	v_lshl_add_u64 v[140:141], v[90:91], 0, v[130:131]
	v_cndmask_b32_e64 v132, 0, v132, s[78:79]
	v_lshlrev_b64 v[140:141], 2, v[140:141]
	s_nop 0
	v_add_f32_dpp v133, v132, v132 quad_perm:[1,0,3,2] row_mask:0xf bank_mask:0xf
	v_lshl_add_u64 v[142:143], s[38:39], 0, v[140:141]
	v_lshl_add_u64 v[144:145], s[40:41], 0, v[140:141]
	v_add_f32_dpp v133, v133, v133 quad_perm:[2,3,0,1] row_mask:0xf bank_mask:0xf
	s_nop 1
	v_add_f32_dpp v133, v133, v133 row_half_mirror row_mask:0xf bank_mask:0xf
	s_nop 1
	v_add_f32_dpp v133, v133, v133 row_mirror row_mask:0xf bank_mask:0xf
	s_nop 1
	v_readlane_b32 s80, v133, 0
	v_readlane_b32 s81, v133, 16
	v_readlane_b32 s82, v133, 32
	v_readlane_b32 s83, v133, 48
	v_mov_b32_e32 v134, s80
	s_nop 0
	v_add_f32_e32 v134, s81, v134
	v_add_f32_e32 v134, s82, v134
	v_add_f32_e32 v134, s83, v134
	v_rcp_f32_e32 v134, v134
	s_nop 0
	v_mul_f32_e32 v135, v132, v134
	s_mov_b64 exec, s[78:79]
	global_store_dword v[142:143], v136, off
	global_store_dword v[144:145], v135, off
	s_mov_b64 exec, s[46:47]
	s_addk_i32 s12, 0x410
	v_lshl_add_u64 v[90:91], v[90:91], 0, s[44:45]
	s_cmpk_lg_i32 s12, 0x4100
	s_cbranch_scc1 .Ltk2_loop
; __device__ void topk_unit(const Params& p, unsigned char* smem, int unit) {
;     ...
;     for (int hf = 0; hf < 2; ++hf) {
;       const int c_ = cnt[hf][0] + cnt[hf][1] + cnt[hf][2] + cnt[hf][3];
;       const unsigned long long bm = __ballot(c_ == 15);
;       const int srcT = __ffsll((long long)bm) - 1;
;       const unsigned T0 = (unsigned)__shfl((int)mxk[hf], srcT);
	v_writelane_b32 v249, s8, 0
	v_writelane_b32 v249, s9, 1
	s_branch .LBB0_1109
.Ltk_retry:
	s_cmp_lg_u32 s10, 0
	s_cbranch_scc1 .Ltk_retry1
	s_sub_i32 s0, s0, 8
	s_sub_i32 s1, s1, 8
	s_lshl_b32 s0, s0, 18
	s_lshl_b32 s1, s1, 18
	s_add_i32 s84, s84, s0
	s_add_i32 s85, s85, s1
	s_mov_b32 s10, 1
	s_branch .Ltk_stepD
.Ltk_retry1:
	s_cmp_eq_u32 s10, 1
	s_cbranch_scc0 .Ltk_fine
	v_max_u32_e32 v6, v2, v3
	v_max_u32_e32 v7, v4, v5
	s_mov_b32 s84, 0
	s_mov_b32 s85, 0
	s_or_b32 s86, s84, 0x80000000
	s_or_b32 s87, s85, 0x80000000
	v_cmp_ge_u32_e64 s[68:69], v6, s86
	v_cmp_ge_u32_e64 s[70:71], v7, s87
	s_bcnt1_i32_b64 s72, s[68:69]
	s_bcnt1_i32_b64 s73, s[70:71]
	s_cmp_ge_u32 s72, 16
	s_cselect_b32 s84, s86, s84
	s_cmp_ge_u32 s73, 16
	s_cselect_b32 s85, s87, s85
	s_or_b32 s86, s84, 0x40000000
	s_or_b32 s87, s85, 0x40000000
	v_cmp_ge_u32_e64 s[68:69], v6, s86
	v_cmp_ge_u32_e64 s[70:71], v7, s87
	s_bcnt1_i32_b64 s72, s[68:69]
	s_bcnt1_i32_b64 s73, s[70:71]
	s_cmp_ge_u32 s72, 16
	s_cselect_b32 s84, s86, s84
	s_cmp_ge_u32 s73, 16
	s_cselect_b32 s85, s87, s85
	s_or_b32 s86, s84, 0x20000000
	s_or_b32 s87, s85, 0x20000000
	v_cmp_ge_u32_e64 s[68:69], v6, s86
	v_cmp_ge_u32_e64 s[70:71], v7, s87
	s_bcnt1_i32_b64 s72, s[68:69]
	s_bcnt1_i32_b64 s73, s[70:71]
	s_cmp_ge_u32 s72, 16
	s_cselect_b32 s84, s86, s84
	s_cmp_ge_u32 s73, 16
	s_cselect_b32 s85, s87, s85
	s_or_b32 s86, s84, 0x10000000
	s_or_b32 s87, s85, 0x10000000
	v_cmp_ge_u32_e64 s[68:69], v6, s86
	v_cmp_ge_u32_e64 s[70:71], v7, s87
	s_bcnt1_i32_b64 s72, s[68:69]
	s_bcnt1_i32_b64 s73, s[70:71]
	s_cmp_ge_u32 s72, 16
	s_cselect_b32 s84, s86, s84
	s_cmp_ge_u32 s73, 16
	s_cselect_b32 s85, s87, s85
	s_or_b32 s86, s84, 0x8000000
	s_or_b32 s87, s85, 0x8000000
	v_cmp_ge_u32_e64 s[68:69], v6, s86
	v_cmp_ge_u32_e64 s[70:71], v7, s87
	s_bcnt1_i32_b64 s72, s[68:69]
	s_bcnt1_i32_b64 s73, s[70:71]
	s_cmp_ge_u32 s72, 16
	s_cselect_b32 s84, s86, s84
	s_cmp_ge_u32 s73, 16
	s_cselect_b32 s85, s87, s85
	s_or_b32 s86, s84, 0x4000000
	s_or_b32 s87, s85, 0x4000000
	v_cmp_ge_u32_e64 s[68:69], v6, s86
	v_cmp_ge_u32_e64 s[70:71], v7, s87
	s_bcnt1_i32_b64 s72, s[68:69]
	s_bcnt1_i32_b64 s73, s[70:71]
	s_cmp_ge_u32 s72, 16
	s_cselect_b32 s84, s86, s84
	s_cmp_ge_u32 s73, 16
	s_cselect_b32 s85, s87, s85
	s_or_b32 s86, s84, 0x2000000
	s_or_b32 s87, s85, 0x2000000
	v_cmp_ge_u32_e64 s[68:69], v6, s86
	v_cmp_ge_u32_e64 s[70:71], v7, s87
	s_bcnt1_i32_b64 s72, s[68:69]
	s_bcnt1_i32_b64 s73, s[70:71]
	s_cmp_ge_u32 s72, 16
	s_cselect_b32 s84, s86, s84
	s_cmp_ge_u32 s73, 16
	s_cselect_b32 s85, s87, s85
	s_or_b32 s86, s84, 0x1000000
	s_or_b32 s87, s85, 0x1000000
	v_cmp_ge_u32_e64 s[68:69], v6, s86
	v_cmp_ge_u32_e64 s[70:71], v7, s87
	s_bcnt1_i32_b64 s72, s[68:69]
	s_bcnt1_i32_b64 s73, s[70:71]
	s_cmp_ge_u32 s72, 16
	s_cselect_b32 s84, s86, s84
	s_cmp_ge_u32 s73, 16
	s_cselect_b32 s85, s87, s85
	s_or_b32 s86, s84, 0x800000
	s_or_b32 s87, s85, 0x800000
	v_cmp_ge_u32_e64 s[68:69], v6, s86
	v_cmp_ge_u32_e64 s[70:71], v7, s87
	s_bcnt1_i32_b64 s72, s[68:69]
	s_bcnt1_i32_b64 s73, s[70:71]
	s_cmp_ge_u32 s72, 16
	s_cselect_b32 s84, s86, s84
	s_cmp_ge_u32 s73, 16
	s_cselect_b32 s85, s87, s85
	s_or_b32 s86, s84, 0x400000
	s_or_b32 s87, s85, 0x400000
	v_cmp_ge_u32_e64 s[68:69], v6, s86
	v_cmp_ge_u32_e64 s[70:71], v7, s87
	s_bcnt1_i32_b64 s72, s[68:69]
	s_bcnt1_i32_b64 s73, s[70:71]
	s_cmp_ge_u32 s72, 16
	s_cselect_b32 s84, s86, s84
	s_cmp_ge_u32 s73, 16
	s_cselect_b32 s85, s87, s85
	s_or_b32 s86, s84, 0x200000
	s_or_b32 s87, s85, 0x200000
	v_cmp_ge_u32_e64 s[68:69], v6, s86
	v_cmp_ge_u32_e64 s[70:71], v7, s87
	s_bcnt1_i32_b64 s72, s[68:69]
	s_bcnt1_i32_b64 s73, s[70:71]
	s_cmp_ge_u32 s72, 16
	s_cselect_b32 s84, s86, s84
	s_cmp_ge_u32 s73, 16
	s_cselect_b32 s85, s87, s85
	s_mov_b32 s10, 2
	s_branch .Ltk_stepD
; __device__ void topk_unit(const Params& p, unsigned char* smem, int unit) {
;     ...
;     for (int hf = 0; hf < 2; ++hf) {
;       const int c_ = cnt[hf][0] + cnt[hf][1] + cnt[hf][2] + cnt[hf][3];
;       const unsigned long long bm = __ballot(c_ == 15);
;       const int srcT = __ffsll((long long)bm) - 1;
;       const unsigned T0 = (unsigned)__shfl((int)mxk[hf], srcT);
.Ltk_fine:
	s_or_b32 s86, s84, 0x100000
	s_or_b32 s87, s85, 0x100000
	v_cmp_ge_u32_e64 s[68:69], v6, s86
	v_cmp_ge_u32_e64 s[70:71], v7, s87
	s_bcnt1_i32_b64 s72, s[68:69]
	s_bcnt1_i32_b64 s73, s[70:71]
	s_cmp_ge_u32 s72, 16
	s_cselect_b32 s84, s86, s84
	s_cmp_ge_u32 s73, 16
	s_cselect_b32 s85, s87, s85
	s_or_b32 s86, s84, 0x80000
	s_or_b32 s87, s85, 0x80000
	v_cmp_ge_u32_e64 s[68:69], v6, s86
	v_cmp_ge_u32_e64 s[70:71], v7, s87
	s_bcnt1_i32_b64 s72, s[68:69]
	s_bcnt1_i32_b64 s73, s[70:71]
	s_cmp_ge_u32 s72, 16
	s_cselect_b32 s84, s86, s84
	s_cmp_ge_u32 s73, 16
	s_cselect_b32 s85, s87, s85
	s_or_b32 s86, s84, 0x40000
	s_or_b32 s87, s85, 0x40000
	v_cmp_ge_u32_e64 s[68:69], v6, s86
	v_cmp_ge_u32_e64 s[70:71], v7, s87
	s_bcnt1_i32_b64 s72, s[68:69]
	s_bcnt1_i32_b64 s73, s[70:71]
	s_cmp_ge_u32 s72, 16
	s_cselect_b32 s84, s86, s84
	s_cmp_ge_u32 s73, 16
	s_cselect_b32 s85, s87, s85
	s_or_b32 s86, s84, 0x20000
	s_or_b32 s87, s85, 0x20000
	v_cmp_ge_u32_e64 s[68:69], v6, s86
	v_cmp_ge_u32_e64 s[70:71], v7, s87
	s_bcnt1_i32_b64 s72, s[68:69]
	s_bcnt1_i32_b64 s73, s[70:71]
	s_cmp_ge_u32 s72, 16
	s_cselect_b32 s84, s86, s84
	s_cmp_ge_u32 s73, 16
	s_cselect_b32 s85, s87, s85
	s_or_b32 s86, s84, 0x10000
	s_or_b32 s87, s85, 0x10000
	v_cmp_ge_u32_e64 s[68:69], v6, s86
	v_cmp_ge_u32_e64 s[70:71], v7, s87
	s_bcnt1_i32_b64 s72, s[68:69]
	s_bcnt1_i32_b64 s73, s[70:71]
	s_cmp_ge_u32 s72, 16
	s_cselect_b32 s84, s86, s84
	s_cmp_ge_u32 s73, 16
	s_cselect_b32 s85, s87, s85
	s_or_b32 s86, s84, 0x8000
	s_or_b32 s87, s85, 0x8000
	v_cmp_ge_u32_e64 s[68:69], v6, s86
	v_cmp_ge_u32_e64 s[70:71], v7, s87
	s_bcnt1_i32_b64 s72, s[68:69]
	s_bcnt1_i32_b64 s73, s[70:71]
	s_cmp_ge_u32 s72, 16
	s_cselect_b32 s84, s86, s84
	s_cmp_ge_u32 s73, 16
	s_cselect_b32 s85, s87, s85
	s_or_b32 s86, s84, 0x4000
	s_or_b32 s87, s85, 0x4000
	v_cmp_ge_u32_e64 s[68:69], v6, s86
	v_cmp_ge_u32_e64 s[70:71], v7, s87
	s_bcnt1_i32_b64 s72, s[68:69]
	s_bcnt1_i32_b64 s73, s[70:71]
	s_cmp_ge_u32 s72, 16
	s_cselect_b32 s84, s86, s84
	s_cmp_ge_u32 s73, 16
	s_cselect_b32 s85, s87, s85
	s_or_b32 s86, s84, 0x2000
	s_or_b32 s87, s85, 0x2000
	v_cmp_ge_u32_e64 s[68:69], v6, s86
	v_cmp_ge_u32_e64 s[70:71], v7, s87
	s_bcnt1_i32_b64 s72, s[68:69]
	s_bcnt1_i32_b64 s73, s[70:71]
	s_cmp_ge_u32 s72, 16
	s_cselect_b32 s84, s86, s84
	s_cmp_ge_u32 s73, 16
	s_cselect_b32 s85, s87, s85
	s_or_b32 s86, s84, 0x1000
	s_or_b32 s87, s85, 0x1000
	v_cmp_ge_u32_e64 s[68:69], v6, s86
	v_cmp_ge_u32_e64 s[70:71], v7, s87
	s_bcnt1_i32_b64 s72, s[68:69]
	s_bcnt1_i32_b64 s73, s[70:71]
	s_cmp_ge_u32 s72, 16
	s_cselect_b32 s84, s86, s84
	s_cmp_ge_u32 s73, 16
	s_cselect_b32 s85, s87, s85
	s_or_b32 s86, s84, 0x800
	s_or_b32 s87, s85, 0x800
	v_cmp_ge_u32_e64 s[68:69], v6, s86
	v_cmp_ge_u32_e64 s[70:71], v7, s87
	s_bcnt1_i32_b64 s72, s[68:69]
	s_bcnt1_i32_b64 s73, s[70:71]
	s_cmp_ge_u32 s72, 16
	s_cselect_b32 s84, s86, s84
	s_cmp_ge_u32 s73, 16
	s_cselect_b32 s85, s87, s85
	s_or_b32 s86, s84, 0x400
	s_or_b32 s87, s85, 0x400
	v_cmp_ge_u32_e64 s[68:69], v6, s86
	v_cmp_ge_u32_e64 s[70:71], v7, s87
	s_bcnt1_i32_b64 s72, s[68:69]
	s_bcnt1_i32_b64 s73, s[70:71]
	s_cmp_ge_u32 s72, 16
	s_cselect_b32 s84, s86, s84
	s_cmp_ge_u32 s73, 16
	s_cselect_b32 s85, s87, s85
	s_or_b32 s86, s84, 0x200
	s_or_b32 s87, s85, 0x200
	v_cmp_ge_u32_e64 s[68:69], v6, s86
	v_cmp_ge_u32_e64 s[70:71], v7, s87
	s_bcnt1_i32_b64 s72, s[68:69]
	s_bcnt1_i32_b64 s73, s[70:71]
	s_cmp_ge_u32 s72, 16
	s_cselect_b32 s84, s86, s84
	s_cmp_ge_u32 s73, 16
	s_cselect_b32 s85, s87, s85
	s_or_b32 s86, s84, 0x100
	s_or_b32 s87, s85, 0x100
	v_cmp_ge_u32_e64 s[68:69], v6, s86
	v_cmp_ge_u32_e64 s[70:71], v7, s87
	s_bcnt1_i32_b64 s72, s[68:69]
	s_bcnt1_i32_b64 s73, s[70:71]
	s_cmp_ge_u32 s72, 16
	s_cselect_b32 s84, s86, s84
	s_cmp_ge_u32 s73, 16
	s_cselect_b32 s85, s87, s85
	s_or_b32 s86, s84, 0x80
	s_or_b32 s87, s85, 0x80
	v_cmp_ge_u32_e64 s[68:69], v6, s86
	v_cmp_ge_u32_e64 s[70:71], v7, s87
	s_bcnt1_i32_b64 s72, s[68:69]
	s_bcnt1_i32_b64 s73, s[70:71]
	s_cmp_ge_u32 s72, 16
	s_cselect_b32 s84, s86, s84
	s_cmp_ge_u32 s73, 16
	s_cselect_b32 s85, s87, s85
	s_or_b32 s86, s84, 64
	s_or_b32 s87, s85, 64
	v_cmp_ge_u32_e64 s[68:69], v6, s86
	v_cmp_ge_u32_e64 s[70:71], v7, s87
	s_bcnt1_i32_b64 s72, s[68:69]
	s_bcnt1_i32_b64 s73, s[70:71]
	s_cmp_ge_u32 s72, 16
	s_cselect_b32 s84, s86, s84
	s_cmp_ge_u32 s73, 16
	s_cselect_b32 s85, s87, s85
	s_or_b32 s86, s84, 32
	s_or_b32 s87, s85, 32
	v_cmp_ge_u32_e64 s[68:69], v6, s86
	v_cmp_ge_u32_e64 s[70:71], v7, s87
	s_bcnt1_i32_b64 s72, s[68:69]
	s_bcnt1_i32_b64 s73, s[70:71]
	s_cmp_ge_u32 s72, 16
	s_cselect_b32 s84, s86, s84
	s_cmp_ge_u32 s73, 16
	s_cselect_b32 s85, s87, s85
	s_or_b32 s86, s84, 16
	s_or_b32 s87, s85, 16
	v_cmp_ge_u32_e64 s[68:69], v6, s86
	v_cmp_ge_u32_e64 s[70:71], v7, s87
	s_bcnt1_i32_b64 s72, s[68:69]
	s_bcnt1_i32_b64 s73, s[70:71]
	s_cmp_ge_u32 s72, 16
	s_cselect_b32 s84, s86, s84
	s_cmp_ge_u32 s73, 16
	s_cselect_b32 s85, s87, s85
	s_or_b32 s86, s84, 8
	s_or_b32 s87, s85, 8
	v_cmp_ge_u32_e64 s[68:69], v6, s86
	v_cmp_ge_u32_e64 s[70:71], v7, s87
	s_bcnt1_i32_b64 s72, s[68:69]
	s_bcnt1_i32_b64 s73, s[70:71]
	s_cmp_ge_u32 s72, 16
	s_cselect_b32 s84, s86, s84
	s_cmp_ge_u32 s73, 16
	s_cselect_b32 s85, s87, s85
	s_or_b32 s86, s84, 4
	s_or_b32 s87, s85, 4
	v_cmp_ge_u32_e64 s[68:69], v6, s86
	v_cmp_ge_u32_e64 s[70:71], v7, s87
	s_bcnt1_i32_b64 s72, s[68:69]
	s_bcnt1_i32_b64 s73, s[70:71]
	s_cmp_ge_u32 s72, 16
	s_cselect_b32 s84, s86, s84
	s_cmp_ge_u32 s73, 16
	s_cselect_b32 s85, s87, s85
	s_or_b32 s86, s84, 2
	s_or_b32 s87, s85, 2
	v_cmp_ge_u32_e64 s[68:69], v6, s86
	v_cmp_ge_u32_e64 s[70:71], v7, s87
	s_bcnt1_i32_b64 s72, s[68:69]
	s_bcnt1_i32_b64 s73, s[70:71]
	s_cmp_ge_u32 s72, 16
	s_cselect_b32 s84, s86, s84
	s_cmp_ge_u32 s73, 16
	s_cselect_b32 s85, s87, s85
	s_or_b32 s86, s84, 1
	s_or_b32 s87, s85, 1
	v_cmp_ge_u32_e64 s[68:69], v6, s86
	v_cmp_ge_u32_e64 s[70:71], v7, s87
	s_bcnt1_i32_b64 s72, s[68:69]
	s_bcnt1_i32_b64 s73, s[70:71]
	s_cmp_ge_u32 s72, 16
	s_cselect_b32 s84, s86, s84
	s_cmp_ge_u32 s73, 16
	s_cselect_b32 s85, s87, s85
	s_mov_b32 s10, 3
	s_branch .Ltk_stepD
